# gemm24 channel-major epilogue: lane pairs exchange packed bf16 via DPP + v_perm so each lane stores one dword instead of two shorts
# baseline (speedup 1.0000x reference)
; #define MFMA(a, b, c) __builtin_amdgcn_mfma_f32_32x32x16_bf16((a), (b), (c), 0, 0, 0)
; DI f32x16 zero16() { f32x16 z; for (int i = 0; i < 16; ++i) z[i] = 0.f; return z; }
;     ...
;   const int fP = r * 128, fsw = (r >> 1) & 7;
;   const int fA = wm * 8192 + fP, fB = 32768 + wn * 16384 + fP;
;   f32x16 acc[2][4];
; #pragma unroll
;   for (int i = 0; i < 2; ++i)
; #pragma unroll
;     for (int j = 0; j < 4; ++j) acc[i][j] = zero16();
;   __syncthreads();
;   G_DMA(0, 0);
;   asm volatile("s_waitcnt vmcnt(0)" ::: "memory");
;   asm volatile("s_waitcnt lgkmcnt(0)" ::: "memory"); __builtin_amdgcn_s_barrier(); asm volatile("" ::: "memory");
;   int cur = 0;
;   for (int s = 0; s < S; ++s) {
;     G_DMA(s + 1, cur ^ BUFB);
;     {
;       const char* Ab = smem + cur + fA;
;       const char* Bb = smem + cur + fB;
;       __builtin_amdgcn_sched_barrier(0);
; #pragma unroll
;       for (int kk = 0; kk < 4; ++kk) {
;         const int ko = (((kk * 2 + hh) ^ fsw) << 4);
;         bf16x8 af[2], wf[4];
;         af[0] = *(const bf16x8*)(Ab + ko); af[1] = *(const bf16x8*)(Ab + 4096 + ko);
; #pragma unroll
;         for (int ni = 0; ni < 4; ++ni) wf[ni] = *(const bf16x8*)(Bb + ni * 4096 + ko);
; #pragma unroll
;         for (int mi = 0; mi < 2; ++mi)
; #pragma unroll
;           for (int ni = 0; ni < 4; ++ni) acc[mi][ni] = MFMA(wf[ni], af[mi], acc[mi][ni]);
;         if (kk == 1) __builtin_amdgcn_sched_barrier(0);
;       }
;       __builtin_amdgcn_sched_barrier(0);
;     }
;     asm volatile("s_waitcnt vmcnt(0)" ::: "memory");
.LBB0_1108:
	v_add3_u32 v215, s6, v187, v189
	v_add3_u32 v244, s6, v188, v189
	v_add_u32_e32 v182, v244, v190
	v_add_u32_e32 v183, v215, v190
	ds_read_b128 v[170:173], v182 offset:32768
	ds_read_b128 v[194:197], v183
	ds_read_b128 v[198:201], v182 offset:36864
	ds_read_b128 v[202:205], v182 offset:40960
	ds_read_b128 v[206:209], v182 offset:45056
	ds_read_b128 v[216:219], v183 offset:4096
	v_add_u32_e32 v184, v244, v191
	v_add_u32_e32 v185, v215, v191
	ds_read_b128 v[220:223], v184 offset:32768
	ds_read_b128 v[236:239], v185
	ds_read_b128 v[224:227], v184 offset:36864
	ds_read_b128 v[228:231], v184 offset:40960
	ds_read_b128 v[232:235], v184 offset:45056
	ds_read_b128 v[240:243], v185 offset:4096
	s_add_i32 s7, s8, 1
	s_mov_b32 s9, s6
	s_cmp_lt_u32 s7, s60
	v_readlane_b32 s6, v253, 59
	s_cselect_b32 s6, s7, s6
	s_lshl_b32 s22, s6, 1
	s_andn2_b32 s22, s22, 31
	s_add_i32 s22, s22, s33
	s_lshr_b32 s23, s22, 4
	s_lshr_b32 s22, s22, 3
	s_and_b32 s22, s22, 12
	v_readlane_b32 s46, v252, 41
	s_and_b32 s23, s23, 0xfffff8
	s_or_b32 s22, s22, s46
	s_or_b32 s24, s23, s74
	s_lshl_b32 s22, s22, 19
	v_readlane_b32 s40, v253, 39
	v_readlane_b32 s41, v253, 40
	s_add_u32 s22, s40, s22
	s_addc_u32 s23, s41, 0
	s_lshl_b32 s6, s6, 7
	s_and_b32 s28, s6, 0x780
	s_add_u32 s22, s22, s28
	s_addc_u32 s23, s23, 0
	s_lshl_b32 s24, s24, 8
	s_ashr_i32 s25, s24, 31
	s_lshl_b64 s[24:25], s[24:25], 11
	s_add_u32 s24, s62, s24
	s_addc_u32 s25, s63, s25
	s_xor_b32 s6, s9, 0x10000
	v_add_u32_e32 v245, s6, v131
	v_lshl_add_u64 v[246:247], s[22:23], 0, v[132:133]
	v_readfirstlane_b32 s22, v245
	v_add_u32_e32 v250, 0x2000, v245
	s_mov_b32 m0, s22
	s_mov_b64 s[42:43], 0x20000
	v_readfirstlane_b32 s22, v250
	v_add_u32_e32 v250, 0x4000, v245
	global_load_lds_dwordx4 v[246:247], off
	s_waitcnt lgkmcnt(10)
	v_mfma_f32_32x32x16_bf16 v[112:127], v[170:173], v[194:197], v[112:127]
	s_waitcnt lgkmcnt(9)
	v_mfma_f32_32x32x16_bf16 v[96:111], v[198:201], v[194:197], v[96:111]
	v_lshl_add_u64 v[248:249], v[246:247], 0, s[42:43]
	s_mov_b32 m0, s22
	s_mov_b64 s[40:41], 0x40000
	v_readfirstlane_b32 s22, v250
	v_add_u32_e32 v250, 0x6000, v245
	global_load_lds_dwordx4 v[248:249], off
	s_waitcnt lgkmcnt(8)
	v_mfma_f32_32x32x16_bf16 v[80:95], v[202:205], v[194:197], v[80:95]
	s_waitcnt lgkmcnt(7)
	v_mfma_f32_32x32x16_bf16 v[64:79], v[206:209], v[194:197], v[64:79]
	v_lshl_add_u64 v[248:249], v[246:247], 0, s[40:41]
	s_mov_b32 m0, s22
	v_readfirstlane_b32 s22, v250
	global_load_lds_dwordx4 v[248:249], off
	s_waitcnt lgkmcnt(6)
	v_mfma_f32_32x32x16_bf16 v[48:63], v[170:173], v[216:219], v[48:63]
	v_mfma_f32_32x32x16_bf16 v[32:47], v[198:201], v[216:219], v[32:47]
	s_mov_b64 s[44:45], 0x60000
	s_mov_b32 m0, s22
	s_add_u32 s22, s24, s28
	v_lshl_add_u64 v[246:247], v[246:247], 0, s[44:45]
	s_addc_u32 s23, s25, 0
	v_add_u32_e32 v250, 0x8000, v245
	global_load_lds_dwordx4 v[246:247], off
	v_mfma_f32_32x32x16_bf16 v[16:31], v[202:205], v[216:219], v[16:31]
	v_mfma_f32_32x32x16_bf16 v[0:15], v[206:209], v[216:219], v[0:15]
	v_lshl_add_u64 v[246:247], s[22:23], 0, v[132:133]
	v_readfirstlane_b32 s22, v250
	v_add_u32_e32 v250, 0xa000, v245
	s_mov_b32 m0, s22
	v_readfirstlane_b32 s22, v250
	v_add_u32_e32 v250, 0xc000, v245
	global_load_lds_dwordx4 v[246:247], off
	v_add_u32_e32 v182, v244, v192
	v_add_u32_e32 v183, v215, v192
	ds_read_b128 v[170:173], v182 offset:32768
	ds_read_b128 v[194:197], v183
	ds_read_b128 v[198:201], v182 offset:36864
	ds_read_b128 v[202:205], v182 offset:40960
	ds_read_b128 v[206:209], v182 offset:45056
	ds_read_b128 v[216:219], v183 offset:4096
	s_waitcnt lgkmcnt(10)
	v_mfma_f32_32x32x16_bf16 v[112:127], v[220:223], v[236:239], v[112:127]
	s_waitcnt lgkmcnt(9)
	v_mfma_f32_32x32x16_bf16 v[96:111], v[224:227], v[236:239], v[96:111]
	v_lshl_add_u64 v[248:249], v[246:247], 0, s[42:43]
	s_mov_b32 m0, s22
	v_readfirstlane_b32 s22, v250
	v_add_u32_e32 v245, 0xe000, v245
	global_load_lds_dwordx4 v[248:249], off
	s_waitcnt lgkmcnt(8)
	v_mfma_f32_32x32x16_bf16 v[80:95], v[228:231], v[236:239], v[80:95]
	s_waitcnt lgkmcnt(7)
	v_mfma_f32_32x32x16_bf16 v[64:79], v[232:235], v[236:239], v[64:79]
	v_lshl_add_u64 v[248:249], v[246:247], 0, s[40:41]
	s_mov_b32 m0, s22
	v_readfirstlane_b32 s22, v245
	global_load_lds_dwordx4 v[248:249], off
	s_waitcnt lgkmcnt(6)
	v_mfma_f32_32x32x16_bf16 v[48:63], v[220:223], v[240:243], v[48:63]
	v_mfma_f32_32x32x16_bf16 v[32:47], v[224:227], v[240:243], v[32:47]
	v_lshl_add_u64 v[246:247], v[246:247], 0, s[44:45]
	s_mov_b32 m0, s22
	s_add_i32 s9, s9, 0
	global_load_lds_dwordx4 v[246:247], off
	v_mfma_f32_32x32x16_bf16 v[16:31], v[228:231], v[240:243], v[16:31]
	v_mfma_f32_32x32x16_bf16 v[0:15], v[232:235], v[240:243], v[0:15]
	v_add_u32_e32 v184, v244, v193
	v_add_u32_e32 v185, v215, v193
	ds_read_b128 v[220:223], v184 offset:32768
	ds_read_b128 v[236:239], v185
	ds_read_b128 v[224:227], v184 offset:36864
	ds_read_b128 v[228:231], v184 offset:40960
	ds_read_b128 v[232:235], v184 offset:45056
	ds_read_b128 v[240:243], v185 offset:4096
	s_waitcnt lgkmcnt(10)
	v_mfma_f32_32x32x16_bf16 v[112:127], v[170:173], v[194:197], v[112:127]
	s_waitcnt lgkmcnt(9)
	v_mfma_f32_32x32x16_bf16 v[96:111], v[198:201], v[194:197], v[96:111]
	s_waitcnt lgkmcnt(8)
	v_mfma_f32_32x32x16_bf16 v[80:95], v[202:205], v[194:197], v[80:95]
	s_waitcnt lgkmcnt(7)
	v_mfma_f32_32x32x16_bf16 v[64:79], v[206:209], v[194:197], v[64:79]
	s_waitcnt lgkmcnt(6)
	v_mfma_f32_32x32x16_bf16 v[48:63], v[170:173], v[216:219], v[48:63]
	v_mfma_f32_32x32x16_bf16 v[32:47], v[198:201], v[216:219], v[32:47]
	v_mfma_f32_32x32x16_bf16 v[16:31], v[202:205], v[216:219], v[16:31]
	v_mfma_f32_32x32x16_bf16 v[0:15], v[206:209], v[216:219], v[0:15]
	s_waitcnt lgkmcnt(4)
	v_mfma_f32_32x32x16_bf16 v[112:127], v[220:223], v[236:239], v[112:127]
	s_waitcnt lgkmcnt(3)
	v_mfma_f32_32x32x16_bf16 v[96:111], v[224:227], v[236:239], v[96:111]
	s_waitcnt lgkmcnt(2)
	v_mfma_f32_32x32x16_bf16 v[80:95], v[228:231], v[236:239], v[80:95]
	s_waitcnt lgkmcnt(1)
	v_mfma_f32_32x32x16_bf16 v[64:79], v[232:235], v[236:239], v[64:79]
	s_waitcnt lgkmcnt(0)
	v_mfma_f32_32x32x16_bf16 v[48:63], v[220:223], v[240:243], v[48:63]
	v_mfma_f32_32x32x16_bf16 v[32:47], v[224:227], v[240:243], v[32:47]
	v_mfma_f32_32x32x16_bf16 v[16:31], v[228:231], v[240:243], v[16:31]
	v_mfma_f32_32x32x16_bf16 v[0:15], v[232:235], v[240:243], v[0:15]
	s_waitcnt vmcnt(0)
	s_and_b32 s9, s8, 15
	s_cmp_lg_u32 s9, 15
	s_cbranch_scc1 .LBB0_1107
; DI unsigned pack2(float a, float b) { f32x2_t v = {a, b}; return __builtin_bit_cast(unsigned, __builtin_convertvector(v, bf16x2_t)); }
;     ...
;             for (int g = 0; g < 4; ++g) {
;               const int n = nt * 256 + wn * 128 + ni * 32 + 8 * g + 4 * hh;
;               const float a0 = acc[mi][ni][4 * g], a1 = acc[mi][ni][4 * g + 1], a2 = acc[mi][ni][4 * g + 2], a3 = acc[mi][ni][4 * g + 3];
;               if (MODE == 0) {
;                 uint2 pk; pk.x = pack2(a0, a1); pk.y = pack2(a2, a3);
;                 if (outp != nullptr && nt >= 32) *(uint2*)(outp + m * 2048 + (n - 8192)) = pk;
;                 else if (n < nvalid) *(uint2*)(C + m * ldc + n) = pk;
;               } else if (MODE == 2) {
;                 const unsigned p01 = pack2(a0, a1), p23 = pack2(a2, a3);
;                 bf16_t* dst = ((nt < 8) ? C : outp) + ((size_t)(n & 2047) * 8 + (m >> 12)) * SEQ + (m & 4095);
;                 dst[0] = (bf16_t)(p01 & 0xffffu); dst[(size_t)8 * SEQ] = (bf16_t)(p01 >> 16);
;                 dst[(size_t)16 * SEQ] = (bf16_t)(p23 & 0xffffu); dst[(size_t)24 * SEQ] = (bf16_t)(p23 >> 16);
	s_lshl_b32 s8, s8, 1
	s_and_b32 s8, s8, 0x7fffffe0
	s_add_i32 s8, s8, s33
	s_lshr_b32 s9, s8, 3
	s_and_b32 s9, s9, 12
	s_or_b32 s9, s9, s46
	s_lshl_b32 s28, s9, 8
	s_cmpk_lt_u32 s8, 0x80
	v_lshl_add_u64 v[170:171], s[28:29], 0, v[134:135]
	s_cselect_b32 s8, s11, s31
	s_cselect_b32 s9, s10, s30
	v_mov_b32_e32 v172, s9
	v_mov_b32_e32 v173, s8
	v_and_b32_e32 v175, 0x7fffffff, v171
	v_and_b32_e32 v174, 0xfffff000, v170
	v_and_b32_e32 v128, 0xfc0, v170
	v_lshl_add_u64 v[172:173], v[174:175], 1, v[172:173]
	v_lshlrev_b32_e32 v128, 1, v128
	v_lshl_add_u64 v[170:171], v[172:173], 0, v[128:129]
	v_mov_b32_e32 v169, v129
	v_lshl_add_u64 v[170:171], v[170:171], 0, v[168:169]
	v_and_b32_e32 v226, 1, v178
	v_mov_b32_e32 v227, 0
	v_cmp_ne_u32_e32 vcc, 0, v226
	v_mov_b32_e32 v228, 0x5040100
	v_mov_b32_e32 v229, 0x3020706
	v_cndmask_b32_e32 v228, v228, v229, vcc
	v_mul_u32_u24_e32 v226, 0xfffe, v226
	s_mov_b32 s9, 0x20000
	v_lshl_add_u64 v[170:171], v[170:171], 0, v[226:227]
	v_cvt_pk_bf16_f32 v216, v112, v113
	v_cvt_pk_bf16_f32 v217, v114, v115
	v_lshl_add_u64 v[222:223], v[170:171], 0, v[136:137]
	v_add_co_u32_e32 v224, vcc, s9, v222
	v_mov_b32_dpp v218, v216 quad_perm:[1,0,3,2] row_mask:0xf bank_mask:0xf
	v_mov_b32_dpp v219, v217 quad_perm:[1,0,3,2] row_mask:0xf bank_mask:0xf
	v_addc_co_u32_e32 v225, vcc, 0, v223, vcc
	v_perm_b32 v220, v218, v216, v228
	v_perm_b32 v221, v219, v217, v228
	global_store_dword v[222:223], v220, off
	global_store_dword v[224:225], v221, off
	v_cvt_pk_bf16_f32 v216, v116, v117
	v_cvt_pk_bf16_f32 v217, v118, v119
	v_lshl_add_u64 v[222:223], v[170:171], 0, v[138:139]
	v_add_co_u32_e32 v224, vcc, s9, v222
	v_mov_b32_dpp v218, v216 quad_perm:[1,0,3,2] row_mask:0xf bank_mask:0xf
	v_mov_b32_dpp v219, v217 quad_perm:[1,0,3,2] row_mask:0xf bank_mask:0xf
	v_addc_co_u32_e32 v225, vcc, 0, v223, vcc
	v_perm_b32 v220, v218, v216, v228
	v_perm_b32 v221, v219, v217, v228
	global_store_dword v[222:223], v220, off
	global_store_dword v[224:225], v221, off
	v_cvt_pk_bf16_f32 v216, v120, v121
	v_cvt_pk_bf16_f32 v217, v122, v123
	v_lshl_add_u64 v[222:223], v[170:171], 0, v[140:141]
	v_add_co_u32_e32 v224, vcc, s9, v222
	v_mov_b32_dpp v218, v216 quad_perm:[1,0,3,2] row_mask:0xf bank_mask:0xf
	v_mov_b32_dpp v219, v217 quad_perm:[1,0,3,2] row_mask:0xf bank_mask:0xf
	v_addc_co_u32_e32 v225, vcc, 0, v223, vcc
	v_perm_b32 v220, v218, v216, v228
	v_perm_b32 v221, v219, v217, v228
	global_store_dword v[222:223], v220, off
	global_store_dword v[224:225], v221, off
	v_cvt_pk_bf16_f32 v216, v124, v125
	v_cvt_pk_bf16_f32 v217, v126, v127
	v_lshl_add_u64 v[222:223], v[170:171], 0, v[142:143]
	v_add_co_u32_e32 v224, vcc, s9, v222
	v_mov_b32_dpp v218, v216 quad_perm:[1,0,3,2] row_mask:0xf bank_mask:0xf
	v_mov_b32_dpp v219, v217 quad_perm:[1,0,3,2] row_mask:0xf bank_mask:0xf
	v_addc_co_u32_e32 v225, vcc, 0, v223, vcc
	v_perm_b32 v220, v218, v216, v228
	v_perm_b32 v221, v219, v217, v228
	global_store_dword v[222:223], v220, off
	global_store_dword v[224:225], v221, off
	v_cvt_pk_bf16_f32 v216, v96, v97
	v_cvt_pk_bf16_f32 v217, v98, v99
	v_lshl_add_u64 v[222:223], v[170:171], 0, v[144:145]
	v_add_co_u32_e32 v224, vcc, s9, v222
	v_mov_b32_dpp v218, v216 quad_perm:[1,0,3,2] row_mask:0xf bank_mask:0xf
	v_mov_b32_dpp v219, v217 quad_perm:[1,0,3,2] row_mask:0xf bank_mask:0xf
	v_addc_co_u32_e32 v225, vcc, 0, v223, vcc
	v_perm_b32 v220, v218, v216, v228
	v_perm_b32 v221, v219, v217, v228
	global_store_dword v[222:223], v220, off
	global_store_dword v[224:225], v221, off
	v_cvt_pk_bf16_f32 v216, v100, v101
	v_cvt_pk_bf16_f32 v217, v102, v103
	v_lshl_add_u64 v[222:223], v[170:171], 0, v[146:147]
	v_add_co_u32_e32 v224, vcc, s9, v222
	v_mov_b32_dpp v218, v216 quad_perm:[1,0,3,2] row_mask:0xf bank_mask:0xf
	v_mov_b32_dpp v219, v217 quad_perm:[1,0,3,2] row_mask:0xf bank_mask:0xf
	v_addc_co_u32_e32 v225, vcc, 0, v223, vcc
	v_perm_b32 v220, v218, v216, v228
	v_perm_b32 v221, v219, v217, v228
	global_store_dword v[222:223], v220, off
	global_store_dword v[224:225], v221, off
	v_cvt_pk_bf16_f32 v216, v104, v105
	v_cvt_pk_bf16_f32 v217, v106, v107
	v_lshl_add_u64 v[222:223], v[170:171], 0, v[148:149]
	v_add_co_u32_e32 v224, vcc, s9, v222
	v_mov_b32_dpp v218, v216 quad_perm:[1,0,3,2] row_mask:0xf bank_mask:0xf
	v_mov_b32_dpp v219, v217 quad_perm:[1,0,3,2] row_mask:0xf bank_mask:0xf
	v_addc_co_u32_e32 v225, vcc, 0, v223, vcc
	v_perm_b32 v220, v218, v216, v228
	v_perm_b32 v221, v219, v217, v228
	global_store_dword v[222:223], v220, off
	global_store_dword v[224:225], v221, off
	v_cvt_pk_bf16_f32 v216, v108, v109
	v_cvt_pk_bf16_f32 v217, v110, v111
	v_lshl_add_u64 v[222:223], v[170:171], 0, v[150:151]
	v_add_co_u32_e32 v224, vcc, s9, v222
	v_mov_b32_dpp v218, v216 quad_perm:[1,0,3,2] row_mask:0xf bank_mask:0xf
	v_mov_b32_dpp v219, v217 quad_perm:[1,0,3,2] row_mask:0xf bank_mask:0xf
	v_addc_co_u32_e32 v225, vcc, 0, v223, vcc
	v_perm_b32 v220, v218, v216, v228
	v_perm_b32 v221, v219, v217, v228
	global_store_dword v[222:223], v220, off
	global_store_dword v[224:225], v221, off
	v_cvt_pk_bf16_f32 v216, v80, v81
	v_cvt_pk_bf16_f32 v217, v82, v83
	v_lshl_add_u64 v[222:223], v[170:171], 0, v[152:153]
	v_add_co_u32_e32 v224, vcc, s9, v222
	v_mov_b32_dpp v218, v216 quad_perm:[1,0,3,2] row_mask:0xf bank_mask:0xf
	v_mov_b32_dpp v219, v217 quad_perm:[1,0,3,2] row_mask:0xf bank_mask:0xf
	v_addc_co_u32_e32 v225, vcc, 0, v223, vcc
	v_perm_b32 v220, v218, v216, v228
	v_perm_b32 v221, v219, v217, v228
	global_store_dword v[222:223], v220, off
	global_store_dword v[224:225], v221, off
	v_cvt_pk_bf16_f32 v216, v84, v85
	v_cvt_pk_bf16_f32 v217, v86, v87
	v_lshl_add_u64 v[222:223], v[170:171], 0, v[154:155]
; DI unsigned pack2(float a, float b) { f32x2_t v = {a, b}; return __builtin_bit_cast(unsigned, __builtin_convertvector(v, bf16x2_t)); }
;     ...
;             for (int g = 0; g < 4; ++g) {
;               const int n = nt * 256 + wn * 128 + ni * 32 + 8 * g + 4 * hh;
;               const float a0 = acc[mi][ni][4 * g], a1 = acc[mi][ni][4 * g + 1], a2 = acc[mi][ni][4 * g + 2], a3 = acc[mi][ni][4 * g + 3];
;               if (MODE == 0) {
;                 uint2 pk; pk.x = pack2(a0, a1); pk.y = pack2(a2, a3);
;                 if (outp != nullptr && nt >= 32) *(uint2*)(outp + m * 2048 + (n - 8192)) = pk;
;                 else if (n < nvalid) *(uint2*)(C + m * ldc + n) = pk;
;               } else if (MODE == 2) {
;                 const unsigned p01 = pack2(a0, a1), p23 = pack2(a2, a3);
;                 bf16_t* dst = ((nt < 8) ? C : outp) + ((size_t)(n & 2047) * 8 + (m >> 12)) * SEQ + (m & 4095);
;                 dst[0] = (bf16_t)(p01 & 0xffffu); dst[(size_t)8 * SEQ] = (bf16_t)(p01 >> 16);
;                 dst[(size_t)16 * SEQ] = (bf16_t)(p23 & 0xffffu); dst[(size_t)24 * SEQ] = (bf16_t)(p23 >> 16);
	v_add_co_u32_e32 v224, vcc, s9, v222
	v_mov_b32_dpp v218, v216 quad_perm:[1,0,3,2] row_mask:0xf bank_mask:0xf
	v_mov_b32_dpp v219, v217 quad_perm:[1,0,3,2] row_mask:0xf bank_mask:0xf
	v_addc_co_u32_e32 v225, vcc, 0, v223, vcc
	v_perm_b32 v220, v218, v216, v228
	v_perm_b32 v221, v219, v217, v228
	global_store_dword v[222:223], v220, off
	global_store_dword v[224:225], v221, off
	v_cvt_pk_bf16_f32 v216, v88, v89
	v_cvt_pk_bf16_f32 v217, v90, v91
	v_lshl_add_u64 v[222:223], v[170:171], 0, v[156:157]
	v_add_co_u32_e32 v224, vcc, s9, v222
	v_mov_b32_dpp v218, v216 quad_perm:[1,0,3,2] row_mask:0xf bank_mask:0xf
	v_mov_b32_dpp v219, v217 quad_perm:[1,0,3,2] row_mask:0xf bank_mask:0xf
	v_addc_co_u32_e32 v225, vcc, 0, v223, vcc
	v_perm_b32 v220, v218, v216, v228
	v_perm_b32 v221, v219, v217, v228
	global_store_dword v[222:223], v220, off
	global_store_dword v[224:225], v221, off
	v_cvt_pk_bf16_f32 v216, v92, v93
	v_cvt_pk_bf16_f32 v217, v94, v95
	v_lshl_add_u64 v[222:223], v[170:171], 0, v[158:159]
	v_add_co_u32_e32 v224, vcc, s9, v222
	v_mov_b32_dpp v218, v216 quad_perm:[1,0,3,2] row_mask:0xf bank_mask:0xf
	v_mov_b32_dpp v219, v217 quad_perm:[1,0,3,2] row_mask:0xf bank_mask:0xf
	v_addc_co_u32_e32 v225, vcc, 0, v223, vcc
	v_perm_b32 v220, v218, v216, v228
	v_perm_b32 v221, v219, v217, v228
	global_store_dword v[222:223], v220, off
	global_store_dword v[224:225], v221, off
	v_cvt_pk_bf16_f32 v216, v64, v65
	v_cvt_pk_bf16_f32 v217, v66, v67
	v_lshl_add_u64 v[222:223], v[170:171], 0, v[160:161]
	v_add_co_u32_e32 v224, vcc, s9, v222
	v_mov_b32_dpp v218, v216 quad_perm:[1,0,3,2] row_mask:0xf bank_mask:0xf
	v_mov_b32_dpp v219, v217 quad_perm:[1,0,3,2] row_mask:0xf bank_mask:0xf
	v_addc_co_u32_e32 v225, vcc, 0, v223, vcc
	v_perm_b32 v220, v218, v216, v228
	v_perm_b32 v221, v219, v217, v228
	global_store_dword v[222:223], v220, off
	global_store_dword v[224:225], v221, off
	v_cvt_pk_bf16_f32 v216, v68, v69
	v_cvt_pk_bf16_f32 v217, v70, v71
	v_lshl_add_u64 v[222:223], v[170:171], 0, v[162:163]
	v_add_co_u32_e32 v224, vcc, s9, v222
	v_mov_b32_dpp v218, v216 quad_perm:[1,0,3,2] row_mask:0xf bank_mask:0xf
	v_mov_b32_dpp v219, v217 quad_perm:[1,0,3,2] row_mask:0xf bank_mask:0xf
	v_addc_co_u32_e32 v225, vcc, 0, v223, vcc
	v_perm_b32 v220, v218, v216, v228
	v_perm_b32 v221, v219, v217, v228
	global_store_dword v[222:223], v220, off
	global_store_dword v[224:225], v221, off
	v_cvt_pk_bf16_f32 v216, v72, v73
	v_cvt_pk_bf16_f32 v217, v74, v75
	v_lshl_add_u64 v[222:223], v[170:171], 0, v[164:165]
	v_add_co_u32_e32 v224, vcc, s9, v222
	v_mov_b32_dpp v218, v216 quad_perm:[1,0,3,2] row_mask:0xf bank_mask:0xf
	v_mov_b32_dpp v219, v217 quad_perm:[1,0,3,2] row_mask:0xf bank_mask:0xf
	v_addc_co_u32_e32 v225, vcc, 0, v223, vcc
	v_perm_b32 v220, v218, v216, v228
	v_perm_b32 v221, v219, v217, v228
	global_store_dword v[222:223], v220, off
	global_store_dword v[224:225], v221, off
	v_cvt_pk_bf16_f32 v216, v76, v77
	v_cvt_pk_bf16_f32 v217, v78, v79
	v_lshl_add_u64 v[222:223], v[170:171], 0, v[166:167]
	v_add_co_u32_e32 v224, vcc, s9, v222
	v_mov_b32_dpp v218, v216 quad_perm:[1,0,3,2] row_mask:0xf bank_mask:0xf
	v_mov_b32_dpp v219, v217 quad_perm:[1,0,3,2] row_mask:0xf bank_mask:0xf
	v_addc_co_u32_e32 v225, vcc, 0, v223, vcc
	v_perm_b32 v220, v218, v216, v228
	v_perm_b32 v221, v219, v217, v228
	global_store_dword v[222:223], v220, off
	global_store_dword v[224:225], v221, off
	v_cvt_pk_bf16_f32 v216, v48, v49
	v_cvt_pk_bf16_f32 v217, v50, v51
	v_lshl_add_u64 v[222:223], v[170:171], 0, v[136:137]
	v_add_co_u32_e32 v224, vcc, s9, v222
	v_mov_b32_dpp v218, v216 quad_perm:[1,0,3,2] row_mask:0xf bank_mask:0xf
	v_mov_b32_dpp v219, v217 quad_perm:[1,0,3,2] row_mask:0xf bank_mask:0xf
	v_addc_co_u32_e32 v225, vcc, 0, v223, vcc
	v_perm_b32 v220, v218, v216, v228
	v_perm_b32 v221, v219, v217, v228
	global_store_dword v[222:223], v220, off offset:64
	global_store_dword v[224:225], v221, off offset:64
	v_cvt_pk_bf16_f32 v216, v52, v53
	v_cvt_pk_bf16_f32 v217, v54, v55
	v_lshl_add_u64 v[222:223], v[170:171], 0, v[138:139]
	v_add_co_u32_e32 v224, vcc, s9, v222
	v_mov_b32_dpp v218, v216 quad_perm:[1,0,3,2] row_mask:0xf bank_mask:0xf
	v_mov_b32_dpp v219, v217 quad_perm:[1,0,3,2] row_mask:0xf bank_mask:0xf
	v_addc_co_u32_e32 v225, vcc, 0, v223, vcc
	v_perm_b32 v220, v218, v216, v228
	v_perm_b32 v221, v219, v217, v228
	global_store_dword v[222:223], v220, off offset:64
	global_store_dword v[224:225], v221, off offset:64
	v_cvt_pk_bf16_f32 v216, v56, v57
	v_cvt_pk_bf16_f32 v217, v58, v59
	v_lshl_add_u64 v[222:223], v[170:171], 0, v[140:141]
	v_add_co_u32_e32 v224, vcc, s9, v222
	v_mov_b32_dpp v218, v216 quad_perm:[1,0,3,2] row_mask:0xf bank_mask:0xf
	v_mov_b32_dpp v219, v217 quad_perm:[1,0,3,2] row_mask:0xf bank_mask:0xf
	v_addc_co_u32_e32 v225, vcc, 0, v223, vcc
	v_perm_b32 v220, v218, v216, v228
	v_perm_b32 v221, v219, v217, v228
	global_store_dword v[222:223], v220, off offset:64
	global_store_dword v[224:225], v221, off offset:64
	v_cvt_pk_bf16_f32 v216, v60, v61
	v_cvt_pk_bf16_f32 v217, v62, v63
	v_lshl_add_u64 v[222:223], v[170:171], 0, v[142:143]
	v_add_co_u32_e32 v224, vcc, s9, v222
	v_mov_b32_dpp v218, v216 quad_perm:[1,0,3,2] row_mask:0xf bank_mask:0xf
	v_mov_b32_dpp v219, v217 quad_perm:[1,0,3,2] row_mask:0xf bank_mask:0xf
	v_addc_co_u32_e32 v225, vcc, 0, v223, vcc
	v_perm_b32 v220, v218, v216, v228
	v_perm_b32 v221, v219, v217, v228
	global_store_dword v[222:223], v220, off offset:64
	global_store_dword v[224:225], v221, off offset:64
	v_cvt_pk_bf16_f32 v216, v32, v33
	v_cvt_pk_bf16_f32 v217, v34, v35
	v_lshl_add_u64 v[222:223], v[170:171], 0, v[144:145]
	v_add_co_u32_e32 v224, vcc, s9, v222
; DI unsigned pack2(float a, float b) { f32x2_t v = {a, b}; return __builtin_bit_cast(unsigned, __builtin_convertvector(v, bf16x2_t)); }
;     ...
;             for (int g = 0; g < 4; ++g) {
;               const int n = nt * 256 + wn * 128 + ni * 32 + 8 * g + 4 * hh;
;               const float a0 = acc[mi][ni][4 * g], a1 = acc[mi][ni][4 * g + 1], a2 = acc[mi][ni][4 * g + 2], a3 = acc[mi][ni][4 * g + 3];
;               if (MODE == 0) {
;                 uint2 pk; pk.x = pack2(a0, a1); pk.y = pack2(a2, a3);
;                 if (outp != nullptr && nt >= 32) *(uint2*)(outp + m * 2048 + (n - 8192)) = pk;
;                 else if (n < nvalid) *(uint2*)(C + m * ldc + n) = pk;
;               } else if (MODE == 2) {
;                 const unsigned p01 = pack2(a0, a1), p23 = pack2(a2, a3);
;                 bf16_t* dst = ((nt < 8) ? C : outp) + ((size_t)(n & 2047) * 8 + (m >> 12)) * SEQ + (m & 4095);
;                 dst[0] = (bf16_t)(p01 & 0xffffu); dst[(size_t)8 * SEQ] = (bf16_t)(p01 >> 16);
;                 dst[(size_t)16 * SEQ] = (bf16_t)(p23 & 0xffffu); dst[(size_t)24 * SEQ] = (bf16_t)(p23 >> 16);
	v_mov_b32_dpp v218, v216 quad_perm:[1,0,3,2] row_mask:0xf bank_mask:0xf
	v_mov_b32_dpp v219, v217 quad_perm:[1,0,3,2] row_mask:0xf bank_mask:0xf
	v_addc_co_u32_e32 v225, vcc, 0, v223, vcc
	v_perm_b32 v220, v218, v216, v228
	v_perm_b32 v221, v219, v217, v228
	global_store_dword v[222:223], v220, off offset:64
	global_store_dword v[224:225], v221, off offset:64
	v_cvt_pk_bf16_f32 v216, v36, v37
	v_cvt_pk_bf16_f32 v217, v38, v39
	v_lshl_add_u64 v[222:223], v[170:171], 0, v[146:147]
	v_add_co_u32_e32 v224, vcc, s9, v222
	v_mov_b32_dpp v218, v216 quad_perm:[1,0,3,2] row_mask:0xf bank_mask:0xf
	v_mov_b32_dpp v219, v217 quad_perm:[1,0,3,2] row_mask:0xf bank_mask:0xf
	v_addc_co_u32_e32 v225, vcc, 0, v223, vcc
	v_perm_b32 v220, v218, v216, v228
	v_perm_b32 v221, v219, v217, v228
	global_store_dword v[222:223], v220, off offset:64
	global_store_dword v[224:225], v221, off offset:64
	v_cvt_pk_bf16_f32 v216, v40, v41
	v_cvt_pk_bf16_f32 v217, v42, v43
	v_lshl_add_u64 v[222:223], v[170:171], 0, v[148:149]
	v_add_co_u32_e32 v224, vcc, s9, v222
	v_mov_b32_dpp v218, v216 quad_perm:[1,0,3,2] row_mask:0xf bank_mask:0xf
	v_mov_b32_dpp v219, v217 quad_perm:[1,0,3,2] row_mask:0xf bank_mask:0xf
	v_addc_co_u32_e32 v225, vcc, 0, v223, vcc
	v_perm_b32 v220, v218, v216, v228
	v_perm_b32 v221, v219, v217, v228
	global_store_dword v[222:223], v220, off offset:64
	global_store_dword v[224:225], v221, off offset:64
	v_cvt_pk_bf16_f32 v216, v44, v45
	v_cvt_pk_bf16_f32 v217, v46, v47
	v_lshl_add_u64 v[222:223], v[170:171], 0, v[150:151]
	v_add_co_u32_e32 v224, vcc, s9, v222
	v_mov_b32_dpp v218, v216 quad_perm:[1,0,3,2] row_mask:0xf bank_mask:0xf
	v_mov_b32_dpp v219, v217 quad_perm:[1,0,3,2] row_mask:0xf bank_mask:0xf
	v_addc_co_u32_e32 v225, vcc, 0, v223, vcc
	v_perm_b32 v220, v218, v216, v228
	v_perm_b32 v221, v219, v217, v228
	global_store_dword v[222:223], v220, off offset:64
	global_store_dword v[224:225], v221, off offset:64
	v_cvt_pk_bf16_f32 v216, v16, v17
	v_cvt_pk_bf16_f32 v217, v18, v19
	v_lshl_add_u64 v[222:223], v[170:171], 0, v[152:153]
	v_add_co_u32_e32 v224, vcc, s9, v222
	v_mov_b32_dpp v218, v216 quad_perm:[1,0,3,2] row_mask:0xf bank_mask:0xf
	v_mov_b32_dpp v219, v217 quad_perm:[1,0,3,2] row_mask:0xf bank_mask:0xf
	v_addc_co_u32_e32 v225, vcc, 0, v223, vcc
	v_perm_b32 v220, v218, v216, v228
	v_perm_b32 v221, v219, v217, v228
	global_store_dword v[222:223], v220, off offset:64
	global_store_dword v[224:225], v221, off offset:64
	v_cvt_pk_bf16_f32 v216, v20, v21
	v_cvt_pk_bf16_f32 v217, v22, v23
	v_lshl_add_u64 v[222:223], v[170:171], 0, v[154:155]
	v_add_co_u32_e32 v224, vcc, s9, v222
	v_mov_b32_dpp v218, v216 quad_perm:[1,0,3,2] row_mask:0xf bank_mask:0xf
	v_mov_b32_dpp v219, v217 quad_perm:[1,0,3,2] row_mask:0xf bank_mask:0xf
	v_addc_co_u32_e32 v225, vcc, 0, v223, vcc
	v_perm_b32 v220, v218, v216, v228
	v_perm_b32 v221, v219, v217, v228
	global_store_dword v[222:223], v220, off offset:64
	global_store_dword v[224:225], v221, off offset:64
	v_cvt_pk_bf16_f32 v216, v24, v25
	v_cvt_pk_bf16_f32 v217, v26, v27
	v_lshl_add_u64 v[222:223], v[170:171], 0, v[156:157]
	v_add_co_u32_e32 v224, vcc, s9, v222
	v_mov_b32_dpp v218, v216 quad_perm:[1,0,3,2] row_mask:0xf bank_mask:0xf
	v_mov_b32_dpp v219, v217 quad_perm:[1,0,3,2] row_mask:0xf bank_mask:0xf
	v_addc_co_u32_e32 v225, vcc, 0, v223, vcc
	v_perm_b32 v220, v218, v216, v228
	v_perm_b32 v221, v219, v217, v228
	global_store_dword v[222:223], v220, off offset:64
	global_store_dword v[224:225], v221, off offset:64
	v_cvt_pk_bf16_f32 v216, v28, v29
	v_cvt_pk_bf16_f32 v217, v30, v31
	v_lshl_add_u64 v[222:223], v[170:171], 0, v[158:159]
	v_add_co_u32_e32 v224, vcc, s9, v222
	v_mov_b32_dpp v218, v216 quad_perm:[1,0,3,2] row_mask:0xf bank_mask:0xf
	v_mov_b32_dpp v219, v217 quad_perm:[1,0,3,2] row_mask:0xf bank_mask:0xf
	v_addc_co_u32_e32 v225, vcc, 0, v223, vcc
	v_perm_b32 v220, v218, v216, v228
	v_perm_b32 v221, v219, v217, v228
	global_store_dword v[222:223], v220, off offset:64
	global_store_dword v[224:225], v221, off offset:64
	v_cvt_pk_bf16_f32 v216, v0, v1
	v_cvt_pk_bf16_f32 v217, v2, v3
	v_lshl_add_u64 v[222:223], v[170:171], 0, v[160:161]
	v_add_co_u32_e32 v224, vcc, s9, v222
	v_mov_b32_dpp v218, v216 quad_perm:[1,0,3,2] row_mask:0xf bank_mask:0xf
	v_mov_b32_dpp v219, v217 quad_perm:[1,0,3,2] row_mask:0xf bank_mask:0xf
	v_addc_co_u32_e32 v225, vcc, 0, v223, vcc
	v_perm_b32 v220, v218, v216, v228
	v_perm_b32 v221, v219, v217, v228
	global_store_dword v[222:223], v220, off offset:64
	global_store_dword v[224:225], v221, off offset:64
; DI unsigned pack2(float a, float b) { f32x2_t v = {a, b}; return __builtin_bit_cast(unsigned, __builtin_convertvector(v, bf16x2_t)); }
; DI f32x16 zero16() { f32x16 z; for (int i = 0; i < 16; ++i) z[i] = 0.f; return z; }
;     ...
;             for (int g = 0; g < 4; ++g) {
;               const int n = nt * 256 + wn * 128 + ni * 32 + 8 * g + 4 * hh;
;               const float a0 = acc[mi][ni][4 * g], a1 = acc[mi][ni][4 * g + 1], a2 = acc[mi][ni][4 * g + 2], a3 = acc[mi][ni][4 * g + 3];
;               if (MODE == 0) {
;                 uint2 pk; pk.x = pack2(a0, a1); pk.y = pack2(a2, a3);
;                 if (outp != nullptr && nt >= 32) *(uint2*)(outp + m * 2048 + (n - 8192)) = pk;
;                 else if (n < nvalid) *(uint2*)(C + m * ldc + n) = pk;
;               } else if (MODE == 2) {
;                 const unsigned p01 = pack2(a0, a1), p23 = pack2(a2, a3);
;                 bf16_t* dst = ((nt < 8) ? C : outp) + ((size_t)(n & 2047) * 8 + (m >> 12)) * SEQ + (m & 4095);
;                 dst[0] = (bf16_t)(p01 & 0xffffu); dst[(size_t)8 * SEQ] = (bf16_t)(p01 >> 16);
;                 dst[(size_t)16 * SEQ] = (bf16_t)(p23 & 0xffffu); dst[(size_t)24 * SEQ] = (bf16_t)(p23 >> 16);
;     ...
; #pragma unroll
;       for (int i = 0; i < 2; ++i)
; #pragma unroll
;         for (int j = 0; j < 4; ++j) acc[i][j] = zero16();
	v_cvt_pk_bf16_f32 v216, v4, v5
	v_cvt_pk_bf16_f32 v217, v6, v7
	v_lshl_add_u64 v[222:223], v[170:171], 0, v[162:163]
	v_add_co_u32_e32 v224, vcc, s9, v222
	v_mov_b32_dpp v218, v216 quad_perm:[1,0,3,2] row_mask:0xf bank_mask:0xf
	v_mov_b32_dpp v219, v217 quad_perm:[1,0,3,2] row_mask:0xf bank_mask:0xf
	v_addc_co_u32_e32 v225, vcc, 0, v223, vcc
	v_perm_b32 v220, v218, v216, v228
	v_perm_b32 v221, v219, v217, v228
	global_store_dword v[222:223], v220, off offset:64
	global_store_dword v[224:225], v221, off offset:64
	v_cvt_pk_bf16_f32 v216, v8, v9
	v_cvt_pk_bf16_f32 v217, v10, v11
	v_lshl_add_u64 v[222:223], v[170:171], 0, v[164:165]
	v_add_co_u32_e32 v224, vcc, s9, v222
	v_mov_b32_dpp v218, v216 quad_perm:[1,0,3,2] row_mask:0xf bank_mask:0xf
	v_mov_b32_dpp v219, v217 quad_perm:[1,0,3,2] row_mask:0xf bank_mask:0xf
	v_addc_co_u32_e32 v225, vcc, 0, v223, vcc
	v_perm_b32 v220, v218, v216, v228
	v_perm_b32 v221, v219, v217, v228
	global_store_dword v[222:223], v220, off offset:64
	global_store_dword v[224:225], v221, off offset:64
	v_cvt_pk_bf16_f32 v216, v12, v13
	v_cvt_pk_bf16_f32 v217, v14, v15
	v_lshl_add_u64 v[222:223], v[170:171], 0, v[166:167]
	v_add_co_u32_e32 v224, vcc, s9, v222
	v_mov_b32_dpp v218, v216 quad_perm:[1,0,3,2] row_mask:0xf bank_mask:0xf
	v_mov_b32_dpp v219, v217 quad_perm:[1,0,3,2] row_mask:0xf bank_mask:0xf
	v_addc_co_u32_e32 v225, vcc, 0, v223, vcc
	v_perm_b32 v220, v218, v216, v228
	v_perm_b32 v221, v219, v217, v228
	global_store_dword v[222:223], v220, off offset:64
	global_store_dword v[224:225], v221, off offset:64
	v_mov_b32_e32 v0, 0
	v_mov_b32_e32 v1, v0
	v_mov_b32_e32 v2, v0
	v_mov_b32_e32 v3, v0
	v_mov_b32_e32 v4, v0
	v_mov_b32_e32 v5, v0
	v_mov_b32_e32 v6, v0
	v_mov_b32_e32 v7, v0
	v_mov_b32_e32 v8, v0
	v_mov_b32_e32 v9, v0
	v_mov_b32_e32 v10, v0
	v_mov_b32_e32 v11, v0
	v_mov_b32_e32 v12, v0
	v_mov_b32_e32 v13, v0
	v_mov_b32_e32 v14, v0
	v_mov_b32_e32 v15, v0
	v_mov_b32_e32 v16, v0
	v_mov_b32_e32 v17, v0
	v_mov_b32_e32 v18, v0
	v_mov_b32_e32 v19, v0
	v_mov_b32_e32 v20, v0
	v_mov_b32_e32 v21, v0
	v_mov_b32_e32 v22, v0
	v_mov_b32_e32 v23, v0
	v_mov_b32_e32 v24, v0
	v_mov_b32_e32 v25, v0
	v_mov_b32_e32 v26, v0
	v_mov_b32_e32 v27, v0
	v_mov_b32_e32 v28, v0
	v_mov_b32_e32 v29, v0
	v_mov_b32_e32 v30, v0
	v_mov_b32_e32 v31, v0
	v_mov_b32_e32 v32, v0
	v_mov_b32_e32 v33, v0
	v_mov_b32_e32 v34, v0
	v_mov_b32_e32 v35, v0
	v_mov_b32_e32 v36, v0
	v_mov_b32_e32 v37, v0
	v_mov_b32_e32 v38, v0
	v_mov_b32_e32 v39, v0
	v_mov_b32_e32 v40, v0
	v_mov_b32_e32 v41, v0
	v_mov_b32_e32 v42, v0
	v_mov_b32_e32 v43, v0
	v_mov_b32_e32 v44, v0
	v_mov_b32_e32 v45, v0
	v_mov_b32_e32 v46, v0
	v_mov_b32_e32 v47, v0
	v_mov_b32_e32 v48, v0
	v_mov_b32_e32 v49, v0
	v_mov_b32_e32 v50, v0
	v_mov_b32_e32 v51, v0
	v_mov_b32_e32 v52, v0
	v_mov_b32_e32 v53, v0
	v_mov_b32_e32 v54, v0
	v_mov_b32_e32 v55, v0
	v_mov_b32_e32 v56, v0
	v_mov_b32_e32 v57, v0
	v_mov_b32_e32 v58, v0
	v_mov_b32_e32 v59, v0
	v_mov_b32_e32 v60, v0
	v_mov_b32_e32 v61, v0
	v_mov_b32_e32 v62, v0
	v_mov_b32_e32 v63, v0
	v_mov_b32_e32 v64, v0
	v_mov_b32_e32 v65, v0
	v_mov_b32_e32 v66, v0
	v_mov_b32_e32 v67, v0
	v_mov_b32_e32 v68, v0
	v_mov_b32_e32 v69, v0
	v_mov_b32_e32 v70, v0
	v_mov_b32_e32 v71, v0
	v_mov_b32_e32 v72, v0
	v_mov_b32_e32 v73, v0
	v_mov_b32_e32 v74, v0
	v_mov_b32_e32 v75, v0
	v_mov_b32_e32 v76, v0
	v_mov_b32_e32 v77, v0
	v_mov_b32_e32 v78, v0
	v_mov_b32_e32 v79, v0
	v_mov_b32_e32 v80, v0
	v_mov_b32_e32 v81, v0
	v_mov_b32_e32 v82, v0
	v_mov_b32_e32 v83, v0
	v_mov_b32_e32 v84, v0
	v_mov_b32_e32 v85, v0
	v_mov_b32_e32 v86, v0
	v_mov_b32_e32 v87, v0
	v_mov_b32_e32 v88, v0
	v_mov_b32_e32 v89, v0
	v_mov_b32_e32 v90, v0
	v_mov_b32_e32 v91, v0
	v_mov_b32_e32 v92, v0
	v_mov_b32_e32 v93, v0
	v_mov_b32_e32 v94, v0
	v_mov_b32_e32 v95, v0
	v_mov_b32_e32 v96, v0
	v_mov_b32_e32 v97, v0
	v_mov_b32_e32 v98, v0
	v_mov_b32_e32 v99, v0
	v_mov_b32_e32 v100, v0
	v_mov_b32_e32 v101, v0
	v_mov_b32_e32 v102, v0
	v_mov_b32_e32 v103, v0
	v_mov_b32_e32 v104, v0
	v_mov_b32_e32 v105, v0
	v_mov_b32_e32 v106, v0
	v_mov_b32_e32 v107, v0
	v_mov_b32_e32 v108, v0
	v_mov_b32_e32 v109, v0
	v_mov_b32_e32 v110, v0
	v_mov_b32_e32 v111, v0
	v_mov_b32_e32 v112, v0
	v_mov_b32_e32 v113, v0
	v_mov_b32_e32 v114, v0
	v_mov_b32_e32 v115, v0
	v_mov_b32_e32 v116, v0
	v_mov_b32_e32 v117, v0
	v_mov_b32_e32 v118, v0
	v_mov_b32_e32 v119, v0
	v_mov_b32_e32 v120, v0
	v_mov_b32_e32 v121, v0
	v_mov_b32_e32 v122, v0
	v_mov_b32_e32 v123, v0
	v_mov_b32_e32 v124, v0
	v_mov_b32_e32 v125, v0
	v_mov_b32_e32 v126, v0
	v_mov_b32_e32 v127, v0
	s_branch .LBB0_1107
